# GEMM-in: main 256x256 GEMM now also covers the 65th row panel (sample rows + allocated padding rows; 3185 tiles, still 13 rounds); the separate 128-row skinny pass is skipped
# speedup vs baseline: 1.0210x; 1.0108x over previous
; #define TID() ({ int t__; asm volatile("v_mbcnt_lo_u32_b32 %0, -1, 0\n\tv_mbcnt_hi_u32_b32 %0, -1, %0" : "=v"(t__)); (wave_u << 6) | t__; })
;     __host__ __device__ bool next(int i, Unit& u) const {
;         const long L = (long)i * G + c; if (L >= nwg) return false;
;         int wgid = (int)L; { const int q = nwg / NXCD, r = nwg % NXCD, xcd = wgid % NXCD, off = wgid / NXCD; wgid = (xcd < r ? xcd * (q + 1) : r * (q + 1) + (xcd - r) * q) + off; }
;         const int nig = WGM * nN, gid = wgid / nig, fm = gid * WGM, gsz = (nM - fm) < WGM ? (nM - fm) : WGM;
;         u.pm = fm + ((wgid % nig) % gsz); u.pn = (wgid % nig) / gsz; return true;
; __global__ __launch_bounds__(NTHREADS, 2) void k_mega(P p) {
;     ...
;             pg8::Gemm g{(const bf16*)(w + WS_H), (const bf16*)(wl + WO_IN), MP, LDP, D}; pg8::StaticOrder S; S.init(MP, LDP, G, (int)blockIdx.x);
;             pg8::EpiBf16<0> E{(bf16*)(w + WS_PROJ), LDP};
;             pg8::gemm_phase<pg8::EpiBf16<0>, pg8::StaticOrder>(lds, g, S, E, nullptr, TID());
.LBB0_180:
	v_writelane_b32 v253, s56, 48
	v_writelane_b32 v254, s54, 0
	s_nop 0
	v_writelane_b32 v253, s57, 49
	v_writelane_b32 v253, s58, 50
	v_writelane_b32 v253, s59, 51
	v_writelane_b32 v253, s60, 52
	v_writelane_b32 v253, s61, 53
	v_writelane_b32 v253, s62, 54
	v_writelane_b32 v253, s63, 55
	v_writelane_b32 v253, s64, 56
	v_writelane_b32 v253, s65, 57
	v_writelane_b32 v253, s66, 58
	v_writelane_b32 v253, s67, 59
	v_writelane_b32 v253, s68, 60
	v_writelane_b32 v253, s69, 61
	v_writelane_b32 v253, s70, 62
	v_writelane_b32 v253, s71, 63
	s_or_b64 exec, exec, s[2:3]
	s_cmpk_lt_i32 s52, 0xc71
	s_cselect_b64 s[0:1], -1, 0
	v_writelane_b32 v254, s0, 1
	s_ashr_i32 s53, s52, 31
	s_ashr_i32 s91, s90, 31
	v_writelane_b32 v254, s1, 2
	s_lshr_b32 s0, s53, 29
	s_add_i32 s0, s52, s0
	s_ashr_i32 s4, s0, 3
	s_and_b32 s0, s0, -8
	s_sub_i32 s5, s52, s0
	s_sub_i32 s0, s90, 64
	s_cmp_gt_i32 s90, 64
	s_cselect_b32 s1, 0xffffffc0, 0
	s_cselect_b32 s8, s0, s90
	s_add_i32 s9, s1, s52
	s_cmp_gt_i32 s9, -1
	s_cselect_b64 s[0:1], -1, 0
	s_cmp_lt_i32 s9, s8
	s_cselect_b64 s[2:3], -1, 0
	s_and_b64 s[0:1], s[0:1], s[2:3]
	s_cmpk_lt_u32 s9, 0x188
	s_cselect_b64 s[2:3], -1, 0
	s_and_b64 s[0:1], s[0:1], s[2:3]
	v_writelane_b32 v254, s0, 3
	s_bitcmp1_b32 s52, 3
	v_readlane_b32 s12, v253, 0
	v_writelane_b32 v254, s1, 4
	s_cselect_b64 s[0:1], -1, 0
	v_writelane_b32 v254, s0, 5
	s_cmpk_lt_i32 s52, 0x100
	v_readlane_b32 s18, v253, 6
	v_writelane_b32 v254, s1, 6
	s_cselect_b64 s[0:1], -1, 0
	v_writelane_b32 v254, s0, 7
	v_readlane_b32 s19, v253, 7
	v_readlane_b32 s13, v253, 1
	v_writelane_b32 v254, s1, 8
	s_add_u32 s0, s18, 0x7080000
	v_writelane_b32 v254, s0, 9
	s_addc_u32 s0, s19, 0
	s_cmpk_lt_i32 s52, 0x400
	v_writelane_b32 v254, s0, 10
	s_cselect_b64 s[0:1], -1, 0
	v_writelane_b32 v254, s0, 11
	s_lshl_b32 s2, s52, 2
	s_ashr_i32 s3, s2, 31
	v_writelane_b32 v254, s1, 12
	s_mov_b32 s0, s2
	v_writelane_b32 v254, s0, 13
	v_readlane_b32 s14, v253, 2
	v_readlane_b32 s15, v253, 3
	v_writelane_b32 v254, s1, 14
	s_lshl_b64 s[0:1], s[2:3], 15
	v_writelane_b32 v254, s0, 15
	s_mul_hi_i32 s61, s96, 0x18000
	v_writelane_b32 v255, s9, 0
	v_writelane_b32 v254, s1, 16
	s_add_u32 s0, s18, 0x17200000
	v_writelane_b32 v254, s0, 17
	s_addc_u32 s0, s19, 0
	v_writelane_b32 v254, s0, 18
	s_add_u32 s0, s18, 0x37200000
	v_writelane_b32 v254, s0, 19
	s_addc_u32 s0, s19, 0
	s_lshl_b64 s[10:11], s[52:53], 16
	v_writelane_b32 v254, s0, 20
	s_add_u32 s0, s18, 0x4080000
	v_writelane_b32 v254, s0, 21
	s_addc_u32 s0, s19, 0
	v_writelane_b32 v254, s0, 22
	s_add_u32 s0, s18, 0x5080000
	v_writelane_b32 v254, s0, 23
	s_addc_u32 s0, s19, 0
	s_lshl_b32 s6, s5, 5
	s_cmp_gt_i32 s52, -1
	v_writelane_b32 v254, s0, 24
	s_cselect_b64 s[0:1], -1, 0
	s_cmp_lt_i32 s52, s90
	s_cselect_b64 s[2:3], -1, 0
	s_and_b64 s[0:1], s[0:1], s[2:3]
	s_cmpk_lt_u32 s52, 0x100
	s_cselect_b64 s[2:3], -1, 0
	s_and_b64 s[0:1], s[0:1], s[2:3]
	v_writelane_b32 v254, s0, 25
	s_movk_i32 s3, 0x18e
	s_mul_i32 s2, s5, 0x81
	v_writelane_b32 v254, s1, 26
	s_lshl_b32 s0, s5, 7
	s_cmp_lt_i32 s5, 0
	s_cselect_b32 s3, s3, 0x18e
	s_mul_i32 s1, s5, 33
	s_mul_i32 s3, s5, s3
	s_cselect_b32 s5, s1, s6
	s_cselect_b32 s2, s2, s0
	s_add_i32 s3, s3, s4
	s_and_b32 s0, s52, 7
	s_addc_u32 s3, s3, 0
	s_mul_hi_i32 s0, s3, 0x5397829d
	s_lshr_b32 s1, s0, 31
	s_ashr_i32 s0, s0, 6
	s_add_i32 s0, s0, s1
	s_mul_i32 s1, s0, 0xc4
	s_sub_i32 s1, s3, s1
	s_lshl_b32 s6, s0, 2
	s_bfe_u32 s0, s1, 0x2001d
	s_add_i32 s3, s1, s0
	s_sext_i32_i16 s7, s3
	s_and_b32 s3, s3, 0xfffc
	s_sub_i32 s1, s1, s3
	s_sext_i32_i16 s1, s1
	s_add_i32 s12, s6, s1
	s_ashr_i32 s1, s7, 2
	v_writelane_b32 v254, s1, 27
	s_mov_b32 s6, s12
	s_lshr_b32 s0, s7, 2
	s_ashr_i32 s13, s12, 31
	v_writelane_b32 v254, s6, 28
	s_bfe_i64 s[0:1], s[0:1], 0x100000
	s_lshl_b64 s[0:1], s[0:1], 19
	v_writelane_b32 v254, s7, 29
	s_lshl_b64 s[6:7], s[12:13], 19
	v_writelane_b32 v254, s6, 30
	s_add_i32 s2, s2, s4
	s_ashr_i32 s97, s96, 31
	v_writelane_b32 v254, s7, 31
	v_writelane_b32 v254, s0, 32
	s_lshl_b64 s[78:79], s[96:97], 14
	s_mul_i32 s60, s96, 0x18000
	v_writelane_b32 v254, s1, 33
	s_add_i32 s0, s5, s4
	s_ashr_i32 s1, s0, 31
	s_lshr_b32 s1, s1, 28
	s_add_i32 s1, s0, s1
	s_ashr_i32 s3, s1, 4
	s_and_b32 s1, s1, 0xfff0
	s_sub_i32 s1, s0, s1
	s_bfe_i32 s0, s1, 0x80000
	s_bfe_u32 s0, s0, 0x2000d
	s_add_i32 s5, s1, s0
	s_bfe_i32 s0, s5, 0x80000
	s_and_b32 s5, s5, 0xfc
	s_sub_i32 s1, s1, s5
	s_lshl_b32 s3, s3, 2
	s_sext_i32_i8 s1, s1
	s_sext_i32_i16 s6, s0
; #define LAS __attribute__((address_space(3)))
; __device__ __forceinline__ void phase_recur1(const P& p, int l, LAS unsigned char* lds, int tid_in, int skip_hgrn1) {
;     unsigned char* ws = p.ws; asm volatile("" : "+s"(ws)); int tid_ = tid_in; asm volatile("" : "+v"(tid_)); const int tid = tid_, G = gridDim.x, wg = blockIdx.x;
;     RecurBufs rb{(bf16*)(ws + WS_PROJ), (bf16*)(ws + WS_XBCC), (float*)(ws + WS_DTV), (float*)(ws + WS_CUM), (float*)(ws + WS_CV), (float*)(ws + WS_SSEG), (float*)(ws + WS_DSEG),
;                  (float*)(ws + WS_HSEG), (float*)(ws + WS_TSEG), (bf16*)(ws + WS_OHG), (bf16*)(ws + WS_Y)};
;     const float* lbs_l = (const float*)(ws + WS_LBS) + l * 1024; float* out = p.out;
;     const float* hgn = p.in[I_HGN] + l * HG_DV;
;     const float* cw = p.in[I_CONVW] + (size_t)l * 4 * SSM_CH; const float* cb = p.in[I_CONVB] + l * SSM_CH; const float* dtb = p.in[I_DTB] + l * SSM_HEADS;
;     const float* alog = p.in[I_ALOG] + l * SSM_HEADS; const float* dsk = p.in[I_DSKIP] + l * SSM_HEADS; const float* ssmn = p.in[I_SSMN] + l * SSM_INNER;
	s_add_i32 s12, s3, s1
	s_ashr_i32 s3, s2, 31
	s_ashr_i32 s1, s6, 2
	s_ashr_i32 s13, s12, 31
	s_lshr_b32 s3, s3, 26
	s_lshr_b32 s0, s6, 2
	v_writelane_b32 v254, s1, 34
	s_lshl_b64 s[6:7], s[12:13], 19
	s_add_i32 s3, s2, s3
	v_writelane_b32 v254, s6, 35
	s_bfe_i64 s[0:1], s[0:1], 0x100000
	s_ashr_i32 s4, s3, 6
	s_and_b32 s3, s3, 0xffc0
	v_writelane_b32 v254, s7, 36
	s_lshl_b64 s[6:7], s[0:1], 19
	s_sub_i32 s3, s2, s3
	v_writelane_b32 v254, s6, 37
	s_bfe_i32 s2, s3, 0x80000
	s_bfe_u32 s2, s2, 0x2000d
	v_writelane_b32 v254, s7, 38
	s_lshl_b64 s[6:7], s[12:13], 20
	v_writelane_b32 v254, s6, 39
	s_add_i32 s5, s3, s2
	s_bfe_i32 s2, s5, 0x80000
	v_writelane_b32 v254, s7, 40
	s_lshl_b64 s[6:7], s[0:1], 20
	s_and_b32 s5, s5, 0xfc
	v_writelane_b32 v254, s6, 41
	s_sub_i32 s3, s3, s5
	s_lshl_b32 s4, s4, 2
	v_writelane_b32 v254, s7, 42
	s_sext_i32_i16 s6, s2
	s_sext_i32_i8 s3, s3
	s_add_i32 s14, s4, s3
	s_ashr_i32 s3, s6, 2
	v_writelane_b32 v254, s3, 43
	s_mov_b32 s4, s14
	s_ashr_i32 s15, s14, 31
	v_writelane_b32 v254, s4, 44
	s_lshr_b32 s2, s6, 2
	s_bfe_i64 s[2:3], s[2:3], 0x100000
	v_writelane_b32 v254, s5, 45
	s_lshl_b64 s[4:5], s[14:15], 19
	v_writelane_b32 v254, s4, 46
	s_lshl_b64 s[2:3], s[2:3], 19
	s_lshl_b64 s[0:1], s[0:1], 21
	v_writelane_b32 v254, s5, 47
	v_writelane_b32 v254, s2, 48
	s_movk_i32 s51, 0x4000
	v_mov_b32_e32 v11, 0
	v_writelane_b32 v254, s3, 49
	s_mov_b32 s2, s12
	v_writelane_b32 v254, s2, 50
	v_mov_b32_e32 v176, 0x358637bd
	v_mov_b32_e32 v178, 0x3ecc95a3
	v_writelane_b32 v254, s3, 51
	s_lshl_b64 s[2:3], s[12:13], 21
	v_writelane_b32 v254, s2, 52
	v_mov_b32_e32 v148, 0x3f317218
	v_mov_b32_e32 v183, 0x7f800000
	v_writelane_b32 v254, s3, 53
	v_writelane_b32 v254, s0, 54
	s_lshl_b64 s[2:3], s[96:97], 11
	v_mov_b32_e32 v184, 0x7fc00000
	v_writelane_b32 v254, s1, 55
	v_readlane_b32 s0, v253, 47
	s_add_i32 s1, s0, 0x4000
	v_writelane_b32 v254, s1, 56
	v_writelane_b32 v254, s2, 57
	s_add_i32 s0, s0, 8
	v_mov_b32_e32 v185, 0xff800000
	v_writelane_b32 v254, s3, 58
	v_writelane_b32 v254, s0, 59
	s_lshl_b64 s[0:1], s[96:97], 15
	v_writelane_b32 v254, s0, 60
	v_mov_b32_e32 v186, 0x41b17218
	v_mov_b32_e32 v187, 0x42a00000
	v_writelane_b32 v254, s1, 61
	s_lshl_b64 s[0:1], s[96:97], 12
	v_writelane_b32 v254, s0, 62
	s_mov_b32 s33, 0x800000
	s_movk_i32 s77, 0x6200
	v_writelane_b32 v254, s1, 63
	s_lshl_b32 s0, s9, 5
	v_writelane_b32 v255, s0, 1
	v_writelane_b32 v255, s8, 2
	s_lshl_b32 s0, s8, 5
	v_writelane_b32 v255, s0, 3
	s_add_u32 s0, s18, s10
	v_writelane_b32 v255, s10, 4
	s_addc_u32 s1, s19, s11
	s_add_u32 s0, s0, 0x7200000
	v_writelane_b32 v255, s11, 5
	v_writelane_b32 v255, s0, 6
	s_addc_u32 s0, s1, 0
	v_writelane_b32 v255, s0, 7
	s_lshl_b32 s0, s52, 4
	v_writelane_b32 v255, s0, 8
	s_lshl_b32 s0, s90, 2
	v_writelane_b32 v255, s0, 9
	s_lshl_b32 s0, s52, 6
	v_writelane_b32 v255, s0, 10
	s_lshl_b32 s0, s90, 6
	v_writelane_b32 v255, s0, 11
	s_add_i32 s0, 0, 0x25f20
	v_writelane_b32 v255, s0, 12
	s_add_i32 s0, 0, 0x25f24
	v_writelane_b32 v255, s0, 13
	s_add_i32 s0, 0, 0x18c00
	v_writelane_b32 v255, s0, 14
	s_add_i32 s0, 0, 0x19000
	v_writelane_b32 v255, s0, 15
	s_add_i32 s0, 0, 0x10400
	v_writelane_b32 v255, s0, 16
	s_add_i32 s0, 0, 0x15400
	v_writelane_b32 v255, s0, 17
	s_add_i32 s0, 0, 0x15800
	v_writelane_b32 v255, s0, 18
	s_add_i32 s0, 0, 0x15600
	v_writelane_b32 v255, s0, 19
	s_add_i32 s0, 0, 0x21c00
	v_writelane_b32 v255, s0, 20
	s_lshl_b64 s[2:3], s[90:91], 16
	v_writelane_b32 v255, s2, 21
	s_add_i32 s76, 0, 0x21400
	s_add_i32 s88, 0, 0x21800
	v_writelane_b32 v255, s3, 22
	v_writelane_b32 v255, s60, 23
	s_movk_i32 s89, 0x410
	s_mov_b32 s54, 0x41a00000
	v_writelane_b32 v255, s61, 24
	v_writelane_b32 v255, s96, 25
	s_mov_b32 s81, 0x7f800000
	s_mov_b32 s75, 0x5040100
	v_writelane_b32 v255, s97, 26
	v_writelane_b32 v255, s78, 27
	s_mov_b32 s38, 0x17788000
	s_mov_b32 s39, 0x1784c000
	s_mov_b32 s55, 0x17789000
	s_mov_b32 s80, 0x1784d000
	s_mov_b32 s74, 0x3f317217
	s_mov_b32 s86, 0xc2a00000
	s_add_i32 s87, 0, 0x15c00
	s_mov_b32 s0, 0
	s_mov_b32 s65, 0
	s_mov_b64 s[94:95], 0x1000
	s_mov_b64 s[82:83], 0x80
	s_mov_b64 s[92:93], 0x3000
	s_mov_b64 s[84:85], 0x31000
	s_mov_b32 s40, 0xbfb8aa3b
	s_mov_b64 s[42:43], 0x10000
	s_mov_b64 s[44:45], 0x2000
	s_mov_b64 s[46:47], 0x600
	s_mov_b64 s[48:49], 0x188000
	s_mov_b64 s[56:57], 0x20000
	v_writelane_b32 v255, s79, 28
	s_waitcnt lgkmcnt(0)
	s_barrier
	v_readlane_b32 s16, v253, 4
	v_readlane_b32 s17, v253, 5
	s_branch .LBB0_183

;     __host__ __device__ bool next(int i, Unit& u) const {
;         const long L = (long)i * G + c; if (L >= nwg) return false;
;         int wgid = (int)L; { const int q = nwg / NXCD, r = nwg % NXCD, xcd = wgid % NXCD, off = wgid / NXCD; wgid = (xcd < r ? xcd * (q + 1) : r * (q + 1) + (xcd - r) * q) + off; }
;         const int nig = WGM * nN, gid = wgid / nig, fm = gid * WGM, gsz = (nM - fm) < WGM ? (nM - fm) : WGM;
;         u.pm = fm + ((wgid % nig) % gsz); u.pn = (wgid % nig) / gsz; return true;
;     }
.LBB0_249:
	s_add_i32 s37, s37, 1
	s_mul_i32 s0, s37, s91
	s_mul_hi_u32 s1, s37, s90
	s_add_i32 s1, s1, s0
	s_mul_i32 s0, s37, s90
	s_add_u32 s16, s0, s52
	s_addc_u32 s17, s1, s53
	v_mov_b64_e32 v[0:1], 0xc71
	v_cmp_lt_i64_e64 s[0:1], s[16:17], v[0:1]
	v_mov_b64_e32 v[0:1], 0xc70
	v_cmp_gt_i64_e32 vcc, s[16:17], v[0:1]
	s_cbranch_vccnz .LBB0_251
	s_ashr_i32 s12, s16, 31
	s_lshr_b32 s12, s12, 29
	s_add_i32 s12, s16, s12
	s_ashr_i32 s13, s12, 3
	s_and_b32 s12, s12, -8
	s_sub_i32 s12, s16, s12
	s_cmp_gt_i32 s12, 0
	s_movk_i32 s14, 0x18e
	s_nop 0
	s_mul_i32 s12, s12, s14
	s_addc_u32 s12, s12, s13
	s_mul_hi_i32 s13, s12, 0x5397829d
	s_lshr_b32 s14, s13, 31
	s_ashr_i32 s13, s13, 6
	s_add_i32 s13, s13, s14
	s_lshl_b32 s14, s13, 2
	s_sub_i32 s15, 0x41, s14
	s_min_i32 s15, s15, 4
	s_abs_i32 s16, s15
	v_cvt_f32_u32_e32 v0, s16
	s_sub_i32 s18, 0, s16
	s_mulk_i32 s13, 0xc4
	s_sub_i32 s13, s12, s13
	v_rcp_iflag_f32_e32 v0, v0
	s_abs_i32 s12, s13
	s_xor_b32 s17, s13, s15
	s_ashr_i32 s17, s17, 31
	v_mul_f32_e32 v0, 0x4f7ffffe, v0
	v_cvt_u32_f32_e32 v0, v0
	s_nop 0
	v_readfirstlane_b32 s19, v0
	s_mul_i32 s18, s18, s19
	s_mul_hi_u32 s18, s19, s18
	s_add_i32 s19, s19, s18
	s_mul_hi_u32 s18, s12, s19
	s_mul_i32 s19, s18, s16
	s_sub_i32 s12, s12, s19
	s_add_i32 s24, s18, 1
	s_sub_i32 s19, s12, s16
	s_cmp_ge_u32 s12, s16
	s_cselect_b32 s18, s24, s18
	s_cselect_b32 s12, s19, s12
	s_add_i32 s19, s18, 1
	s_cmp_ge_u32 s12, s16
	s_cselect_b32 s12, s19, s18
	s_xor_b32 s12, s12, s17
	s_sub_i32 s12, s12, s17
	s_mul_i32 s15, s12, s15
	s_sub_i32 s13, s13, s15
	s_add_i32 s14, s14, s13

; #define LAS __attribute__((address_space(3)))
; #define TID() ({ int t__; asm volatile("v_mbcnt_lo_u32_b32 %0, -1, 0\n\tv_mbcnt_hi_u32_b32 %0, -1, %0" : "=v"(t__)); (wave_u << 6) | t__; })
; template <int RT, class Epi>
; __device__ __forceinline__ void skinny_gemm(const bf16* A, size_t lda, const bf16* Bt, int K, int N, const Epi& epi, int wg, int wg_first, int wg_count, int tid, LAS unsigned char* lds) {
;     const int lane = tid & 63, w = tid >> 6, c = lane & 15, g = lane >> 4;
;     constexpr int NRG = 8 / RT;
;     const int nunit = (N / 32) * NRG, ksteps = K / 256;
;     int me = wg - wg_first; if (me < 0 || me >= wg_count) return;
;     for (int s = me; s < nunit; s += wg_count) {
;         const int n0 = 32 * (s / NRG), r0 = (s % NRG) * (16 * RT);
;         f32x4 acc[RT][2];
; #pragma unroll
;         for (int rt = 0; rt < RT; ++rt) { acc[rt][0] = (f32x4){0.f, 0.f, 0.f, 0.f}; acc[rt][1] = (f32x4){0.f, 0.f, 0.f, 0.f}; }
;         const bf16* ap = A + (size_t)(r0 + c) * lda + (size_t)w * (K / 8) + 8 * g;
;         const bf16* bp = Bt + (size_t)(n0 + c) * K + (size_t)w * (K / 8) + 8 * g;
; __global__ __launch_bounds__(NTHREADS, 2) void k_mega(P p) {
;     ...
;             const int skf = G > 64 ? 64 : 0, skn = G > 64 ? G - 64 : G; skinny_gemm<8>((const bf16*)(w + WS_H) + (size_t)MP * D, D, (const bf16*)(wl + WO_IN), D, LDP, SkStoreBf16{(bf16*)(w + WS_PROJ) + (size_t)MP * LDP, LDP, 0}, (int)blockIdx.x, skf, skn, TID(), lds); } }
.LBB0_259:
	v_readlane_b32 s0, v254, 3
	v_readlane_b32 s1, v254, 4
	s_andn2_b64 vcc, exec, s[0:1]
	v_mbcnt_lo_u32_b32 v0, -1, 0
	v_mbcnt_hi_u32_b32 v0, -1, v0
	s_branch .LBB0_262
	v_readlane_b32 s0, v254, 0
	v_and_b32_e32 v149, 15, v0
	v_lshlrev_b32_e32 v10, 11, v149
	v_or_b32_e32 v1, s0, v0
	v_ashrrev_i32_e32 v2, 6, v1
	v_ashrrev_i32_e32 v3, 31, v2
	v_bfe_u32 v12, v0, 4, 2
	v_lshl_add_u64 v[4:5], s[2:3], 0, v[10:11]
	v_lshlrev_b64 v[6:7], 8, v[2:3]
	v_lshl_add_u64 v[4:5], v[4:5], 0, v[6:7]
	v_lshlrev_b32_e32 v10, 4, v12
	v_lshl_add_u64 v[4:5], v[4:5], 0, v[10:11]
	s_mov_b64 s[0:1], 0x17500000
	v_lshl_add_u64 v[8:9], v[4:5], 0, s[0:1]
	s_mov_b64 s[0:1], 0x17508000
	v_lshl_add_u64 v[90:91], v[4:5], 0, s[0:1]
	s_mov_b64 s[0:1], 0x17510000
	v_lshl_add_u64 v[92:93], v[4:5], 0, s[0:1]
	s_mov_b64 s[0:1], 0x17518000
	v_lshl_add_u64 v[94:95], v[4:5], 0, s[0:1]
	s_mov_b64 s[0:1], 0x17520000
	v_lshl_add_u64 v[96:97], v[4:5], 0, s[0:1]
	s_mov_b64 s[0:1], 0x17528000
	v_lshl_add_u64 v[98:99], v[4:5], 0, s[0:1]
	s_mov_b64 s[0:1], 0x17530000
	v_lshl_add_u64 v[100:101], v[4:5], 0, s[0:1]
	s_mov_b64 s[0:1], 0x17538000
	v_lshl_add_u64 v[102:103], v[4:5], 0, s[0:1]
	s_mov_b64 s[0:1], 0x17508040
	v_lshl_add_u64 v[104:105], v[4:5], 0, s[0:1]
	s_mov_b64 s[0:1], 0x17510040
	v_lshl_add_u64 v[106:107], v[4:5], 0, s[0:1]
	s_mov_b64 s[0:1], 0x17518040
	v_lshl_add_u64 v[108:109], v[4:5], 0, s[0:1]
	s_mov_b64 s[0:1], 0x17520040
	v_lshl_add_u64 v[110:111], v[4:5], 0, s[0:1]
	s_mov_b64 s[0:1], 0x17528040
	v_lshl_add_u64 v[112:113], v[4:5], 0, s[0:1]
	s_mov_b64 s[0:1], 0x17530040
	v_lshl_add_u64 v[114:115], v[4:5], 0, s[0:1]
	s_mov_b64 s[0:1], 0x17538040
	v_lshl_add_u64 v[116:117], v[4:5], 0, s[0:1]
	s_mov_b64 s[0:1], 0x17508080
	v_lshl_add_u64 v[118:119], v[4:5], 0, s[0:1]
	s_mov_b64 s[0:1], 0x17510080
	v_lshl_add_u64 v[120:121], v[4:5], 0, s[0:1]
	s_mov_b64 s[0:1], 0x17518080
	v_lshl_add_u64 v[122:123], v[4:5], 0, s[0:1]
	s_mov_b64 s[0:1], 0x17520080
	v_lshl_add_u64 v[124:125], v[4:5], 0, s[0:1]
	s_mov_b64 s[0:1], 0x17528080
	v_lshl_add_u64 v[126:127], v[4:5], 0, s[0:1]
	s_mov_b64 s[0:1], 0x17530080
	v_lshl_add_u64 v[128:129], v[4:5], 0, s[0:1]
	s_mov_b64 s[0:1], 0x17538080
	v_lshl_add_u64 v[130:131], v[4:5], 0, s[0:1]
	s_mov_b64 s[0:1], 0x175080c0
	v_lshl_add_u64 v[132:133], v[4:5], 0, s[0:1]
	s_mov_b64 s[0:1], 0x175100c0
	v_lshl_add_u64 v[134:135], v[4:5], 0, s[0:1]
	s_mov_b64 s[0:1], 0x175180c0
	v_lshl_add_u64 v[6:7], s[4:5], 0, v[6:7]
	v_lshlrev_b32_e32 v0, 3, v0
	v_lshl_add_u64 v[136:137], v[4:5], 0, s[0:1]
	s_mov_b64 s[0:1], 0x175200c0
	v_lshl_add_u64 v[88:89], v[6:7], 0, v[10:11]
	v_ashrrev_i32_e32 v6, 2, v1
	v_and_b32_e32 v156, 24, v0
	v_lshl_add_u64 v[138:139], v[4:5], 0, s[0:1]
	s_mov_b64 s[0:1], 0x175280c0
	v_lshlrev_b32_e32 v0, 7, v6
	v_lshlrev_b32_e32 v1, 2, v156
	v_lshl_add_u64 v[140:141], v[4:5], 0, s[0:1]
	s_mov_b64 s[0:1], 0x175300c0
	v_add3_u32 v157, 0, v0, v1
	v_lshl_add_u64 v[142:143], v[4:5], 0, s[0:1]
	s_mov_b64 s[0:1], 0x175380c0
	v_mov_b64_e32 v[0:1], s[2:3]
	v_lshl_add_u64 v[144:145], v[4:5], 0, s[0:1]
	v_mad_i64_i32 v[0:1], s[0:1], v6, s77, v[0:1]
	v_lshl_add_u32 v13, v149, 2, 0
	v_lshlrev_b32_e32 v2, 14, v2
	v_lshlrev_b32_e32 v3, 9, v12
	s_mov_b64 s[0:1], 0x2fe00000
	v_add3_u32 v158, v13, v2, v3
	v_add_u32_e32 v159, 0x10000, v157
	v_add_u32_e32 v160, 0x10010, v157
	v_add_u32_e32 v161, 0x14000, v157
	v_add_u32_e32 v162, 0x14010, v157
	v_add_u32_e32 v163, 0x18000, v157
	v_add_u32_e32 v164, 0x18010, v157
	v_add_u32_e32 v165, 0x1c000, v157
	v_add_u32_e32 v166, 0x1c010, v157
	v_lshl_add_u64 v[146:147], v[0:1], 0, s[0:1]
	v_readlane_b32 s0, v255, 1
	v_readlane_b32 s1, v255, 0
	v_readlane_b32 s2, v255, 2
	v_readlane_b32 s3, v255, 3
